# v18 + the pooling stage of the even-layer sample mixer also split over the workgroup pair (each workgroup loads, pools and stores only its own channel half)
# baseline (speedup 1.0000x reference)
; #define LAS __attribute__((address_space(3)))
; __device__ __forceinline__ float dot4(f32x4 a, f32x4 b) { return (a[0] * b[0] + a[1] * b[1]) + (a[2] * b[2] + a[3] * b[3]); }
; __device__ __forceinline__ void unpack8(u32x4 w, f32x4& a, f32x4& b) { a = (f32x4){bflo(w.x), bfhi(w.x), bflo(w.y), bfhi(w.y)}; b = (f32x4){bflo(w.z), bfhi(w.z), bflo(w.w), bfhi(w.w)}; }
; __device__ __forceinline__ void sample_mix_even(Frame& F0, int j, int b) {
;     ...
;     __syncthreads();
;     float tot = 0.f;
; #pragma unroll
;     for (int i = 0; i < 8; ++i) tot += red[i];
;     const float rv = rsqrtf(tot * (1.0f / D) + EPS);
; #pragma unroll
;     for (int k = 0; k < 2; ++k) {
;         const int d = tid + 512 * k, g = d >> 8, dd = d & 255;
;         const bf16_t* pm = ((bf16_t*)(F.ws + WS_PMT)) + (size_t)(j * 4 + g) * 65536 + (size_t)dd * 256; const LAS float* pg = pl + g * 256;
;         float a = 0.f;
; #pragma unroll
;         for (int hb = 0; hb < 2; ++hb) {
;             u32x4 pr[16];
; #pragma unroll
;             for (int i = 0; i < 16; ++i) pr[i] = *(const u32x4*)(pm + hb * 128 + i * 8);
; #pragma unroll
;             for (int i = 0; i < 16; ++i) { f32x4 p0, p1; unpack8(pr[i], p0, p1); const LAS float* q = pg + hb * 128 + i * 8; a += dot4(p0, *(const LAS f32x4*)q) + dot4(p1, *(const LAS f32x4*)(q + 4)); }
.Lpool_join:
	s_waitcnt lgkmcnt(0)
	s_barrier
	s_cmp_eq_u32 s100, 0
	s_cbranch_scc0 .Lsmx_hi
	global_load_dwordx4 v[40:43], v[56:57], off
	global_load_dwordx4 v[44:47], v[56:57], off offset:16
	ds_read_b128 v[0:3], v201 offset:4096
	ds_read_b128 v[4:7], v201 offset:4112
	global_load_dwordx4 v[64:67], v[56:57], off offset:32
	global_load_dwordx4 v[68:71], v[56:57], off offset:48
	s_mov_b32 s4, 0x800000
	s_waitcnt lgkmcnt(1)
	v_add_f32_e32 v0, 0, v0
	v_add_f32_e32 v0, v0, v1
	v_add_f32_e32 v0, v0, v2
	v_add_f32_e32 v0, v0, v3
	s_waitcnt lgkmcnt(0)
	v_add_f32_e32 v0, v0, v4
	v_add_f32_e32 v0, v0, v5
	v_add_f32_e32 v0, v0, v6
	v_add_f32_e32 v0, v0, v7
	v_mov_b32_e32 v1, 0x358637bd
	v_fmamk_f32 v0, v0, 0x3a800000, v1
	v_cmp_gt_f32_e32 vcc, s4, v0
	v_mul_f32_e32 v1, 0x4b800000, v0
	s_load_dwordx8 s[4:11], s[14:15], 0x60
	v_cndmask_b32_e32 v0, v0, v1, vcc
	v_rsq_f32_e32 v0, v0
	s_lshl_b64 s[14:15], s[16:17], 12
	s_add_u32 s2, s2, s14
	s_addc_u32 s3, s3, s15
	v_mul_f32_e32 v1, 0x45800000, v0
	v_cndmask_b32_e32 v59, v0, v1, vcc
	v_and_b32_e32 v0, 0x3fffff00, v48
	v_lshl_add_u32 v63, v0, 2, 0
	global_load_dwordx4 v[32:35], v[56:57], off offset:112
	global_load_dwordx4 v[36:39], v[56:57], off offset:96
	global_load_dwordx4 v[72:75], v[56:57], off offset:80
	global_load_dwordx4 v[76:79], v[56:57], off offset:64
	global_load_dwordx4 v[16:19], v[56:57], off offset:176
	global_load_dwordx4 v[20:23], v[56:57], off offset:160
	global_load_dwordx4 v[24:27], v[56:57], off offset:144
	global_load_dwordx4 v[28:31], v[56:57], off offset:128
	global_load_dwordx4 v[0:3], v[56:57], off offset:240
	global_load_dwordx4 v[4:7], v[56:57], off offset:224
	global_load_dwordx4 v[8:11], v[56:57], off offset:208
	global_load_dwordx4 v[12:15], v[56:57], off offset:192
	ds_read_b128 v[80:83], v63
	s_lshl_b64 s[0:1], s[0:1], 12
	s_add_u32 s0, s12, s0
	s_addc_u32 s1, s13, s1
	s_add_i32 s93, s93, s22
	s_cmp_lt_i32 s93, 16
	s_waitcnt vmcnt(15)
	v_lshlrev_b32_e32 v92, 16, v40
	v_and_b32_e32 v93, 0xffff0000, v40
	v_lshlrev_b32_e32 v94, 16, v41
	v_and_b32_e32 v95, 0xffff0000, v41
	v_lshlrev_b32_e32 v96, 16, v42
	v_and_b32_e32 v97, 0xffff0000, v42
	v_lshlrev_b32_e32 v98, 16, v43
	v_and_b32_e32 v99, 0xffff0000, v43
	ds_read_b128 v[40:43], v63 offset:16
	ds_read_b128 v[84:87], v63 offset:32
	ds_read_b128 v[88:91], v63 offset:48
	s_waitcnt lgkmcnt(0)
	v_mul_f32_e32 v81, v81, v93
	v_fmac_f32_e32 v81, v80, v92
	v_mul_f32_e32 v41, v41, v97
	v_fmac_f32_e32 v41, v40, v96
	v_mul_f32_e32 v40, v43, v99
	v_mul_f32_e32 v80, v83, v95
	v_fmac_f32_e32 v40, v42, v98
	s_waitcnt vmcnt(14)
	v_and_b32_e32 v42, 0xffff0000, v44
	v_fmac_f32_e32 v80, v82, v94
	v_add_f32_e32 v40, v41, v40
	v_lshlrev_b32_e32 v41, 16, v44
	v_and_b32_e32 v44, 0xffff0000, v45
	v_mul_f32_e32 v42, v85, v42
	v_add_f32_e32 v80, v81, v80
	v_lshlrev_b32_e32 v43, 16, v45
	v_fmac_f32_e32 v42, v84, v41
	v_mul_f32_e32 v41, v87, v44
	v_add_f32_e32 v40, v80, v40
	v_lshlrev_b32_e32 v45, 16, v46
	v_and_b32_e32 v46, 0xffff0000, v46
	v_lshlrev_b32_e32 v80, 16, v47
	v_and_b32_e32 v47, 0xffff0000, v47
	v_fmac_f32_e32 v41, v86, v43
	v_add_f32_e32 v41, v42, v41
	v_mul_f32_e32 v42, v89, v46
	v_mul_f32_e32 v43, v91, v47
	v_fmac_f32_e32 v42, v88, v45
	v_fmac_f32_e32 v43, v90, v80
	v_add_f32_e32 v42, v42, v43
	v_add_f32_e32 v40, 0, v40
	v_add_f32_e32 v41, v41, v42
	v_add_f32_e32 v80, v40, v41
	ds_read_b128 v[40:43], v63 offset:64
	s_waitcnt vmcnt(13)
	v_and_b32_e32 v44, 0xffff0000, v64
	v_lshlrev_b32_e32 v81, 16, v64
	v_lshlrev_b32_e32 v64, 16, v65
	v_and_b32_e32 v65, 0xffff0000, v65
	s_waitcnt lgkmcnt(0)
	v_mul_f32_e32 v41, v41, v44
	ds_read_b128 v[44:47], v63 offset:80
	v_fmac_f32_e32 v41, v40, v81
	v_mul_f32_e32 v40, v43, v65
	v_lshlrev_b32_e32 v82, 16, v66
	v_and_b32_e32 v66, 0xffff0000, v66
	v_lshlrev_b32_e32 v83, 16, v67
	v_and_b32_e32 v67, 0xffff0000, v67
	v_fmac_f32_e32 v40, v42, v64
	v_add_f32_e32 v40, v41, v40
	s_waitcnt lgkmcnt(0)
	v_mul_f32_e32 v41, v45, v66
	v_mul_f32_e32 v42, v47, v67
	v_fmac_f32_e32 v41, v44, v82
	v_fmac_f32_e32 v42, v46, v83
	v_add_f32_e32 v41, v41, v42
	v_add_f32_e32 v40, v40, v41
	v_add_f32_e32 v64, v80, v40
	ds_read_b128 v[40:43], v63 offset:96
	s_waitcnt vmcnt(12)
	v_and_b32_e32 v44, 0xffff0000, v68
	v_lshlrev_b32_e32 v65, 16, v68
	v_and_b32_e32 v67, 0xffff0000, v69
	v_lshlrev_b32_e32 v66, 16, v69
	s_waitcnt lgkmcnt(0)
	v_mul_f32_e32 v41, v41, v44
	ds_read_b128 v[44:47], v63 offset:112
	v_fmac_f32_e32 v41, v40, v65
	v_mul_f32_e32 v40, v43, v67
	v_lshlrev_b32_e32 v68, 16, v70
	v_and_b32_e32 v69, 0xffff0000, v70
	v_lshlrev_b32_e32 v70, 16, v71
	v_and_b32_e32 v71, 0xffff0000, v71
	v_fmac_f32_e32 v40, v42, v66
	v_add_f32_e32 v40, v41, v40
	s_waitcnt lgkmcnt(0)
	v_mul_f32_e32 v41, v45, v69
	v_mul_f32_e32 v42, v47, v71
	v_fmac_f32_e32 v41, v44, v68
	v_fmac_f32_e32 v42, v46, v70
	v_add_f32_e32 v41, v41, v42
	v_add_f32_e32 v40, v40, v41
	v_add_f32_e32 v64, v64, v40
	ds_read_b128 v[40:43], v63 offset:128
	s_waitcnt vmcnt(8)
	v_and_b32_e32 v44, 0xffff0000, v76
	v_lshlrev_b32_e32 v65, 16, v76
	v_and_b32_e32 v67, 0xffff0000, v77
	v_lshlrev_b32_e32 v66, 16, v77
	s_waitcnt lgkmcnt(0)
	v_mul_f32_e32 v41, v41, v44
	ds_read_b128 v[44:47], v63 offset:144
	v_fmac_f32_e32 v41, v40, v65
	v_mul_f32_e32 v40, v43, v67
	v_and_b32_e32 v69, 0xffff0000, v78
	v_and_b32_e32 v71, 0xffff0000, v79
	v_fmac_f32_e32 v40, v42, v66
	v_lshlrev_b32_e32 v68, 16, v78
	v_lshlrev_b32_e32 v70, 16, v79
	v_add_f32_e32 v40, v41, v40
	s_waitcnt lgkmcnt(0)
	v_mul_f32_e32 v41, v45, v69
	v_mul_f32_e32 v42, v47, v71
	v_fmac_f32_e32 v41, v44, v68
	v_fmac_f32_e32 v42, v46, v70
	v_add_f32_e32 v41, v41, v42
	v_add_f32_e32 v40, v40, v41
	v_add_f32_e32 v64, v64, v40
	ds_read_b128 v[40:43], v63 offset:160
	v_and_b32_e32 v44, 0xffff0000, v72
	v_lshlrev_b32_e32 v65, 16, v72
	v_and_b32_e32 v67, 0xffff0000, v73
	v_lshlrev_b32_e32 v66, 16, v73
	s_waitcnt lgkmcnt(0)
; #define LAS __attribute__((address_space(3)))
; __device__ __forceinline__ float dot4(f32x4 a, f32x4 b) { return (a[0] * b[0] + a[1] * b[1]) + (a[2] * b[2] + a[3] * b[3]); }
; __device__ __forceinline__ void unpack8(u32x4 w, f32x4& a, f32x4& b) { a = (f32x4){bflo(w.x), bfhi(w.x), bflo(w.y), bfhi(w.y)}; b = (f32x4){bflo(w.z), bfhi(w.z), bflo(w.w), bfhi(w.w)}; }
; __device__ __forceinline__ void sample_mix_even(Frame& F0, int j, int b) {
;     ...
;         for (int hb = 0; hb < 2; ++hb) {
;             u32x4 pr[16];
; #pragma unroll
;             for (int i = 0; i < 16; ++i) pr[i] = *(const u32x4*)(pm + hb * 128 + i * 8);
; #pragma unroll
;             for (int i = 0; i < 16; ++i) { f32x4 p0, p1; unpack8(pr[i], p0, p1); const LAS float* q = pg + hb * 128 + i * 8; a += dot4(p0, *(const LAS f32x4*)q) + dot4(p1, *(const LAS f32x4*)(q + 4)); }
	v_mul_f32_e32 v41, v41, v44
	ds_read_b128 v[44:47], v63 offset:176
	v_fmac_f32_e32 v41, v40, v65
	v_mul_f32_e32 v40, v43, v67
	v_and_b32_e32 v69, 0xffff0000, v74
	v_and_b32_e32 v71, 0xffff0000, v75
	v_fmac_f32_e32 v40, v42, v66
	v_lshlrev_b32_e32 v68, 16, v74
	v_lshlrev_b32_e32 v70, 16, v75
	v_add_f32_e32 v40, v41, v40
	s_waitcnt lgkmcnt(0)
	v_mul_f32_e32 v41, v45, v69
	v_mul_f32_e32 v42, v47, v71
	v_fmac_f32_e32 v41, v44, v68
	v_fmac_f32_e32 v42, v46, v70
	v_add_f32_e32 v41, v41, v42
	v_add_f32_e32 v40, v40, v41
	v_add_f32_e32 v44, v64, v40
	ds_read_b128 v[40:43], v63 offset:192
	v_lshlrev_b32_e32 v45, 16, v36
	v_and_b32_e32 v36, 0xffff0000, v36
	v_lshlrev_b32_e32 v46, 16, v37
	v_and_b32_e32 v47, 0xffff0000, v37
	v_lshlrev_b32_e32 v64, 16, v38
	v_and_b32_e32 v65, 0xffff0000, v38
	v_lshlrev_b32_e32 v66, 16, v39
	v_and_b32_e32 v67, 0xffff0000, v39
	s_waitcnt lgkmcnt(0)
	v_mul_f32_e32 v41, v41, v36
	ds_read_b128 v[36:39], v63 offset:208
	v_fmac_f32_e32 v41, v40, v45
	v_mul_f32_e32 v40, v43, v47
	v_fmac_f32_e32 v40, v42, v46
	v_add_f32_e32 v40, v41, v40
	s_waitcnt lgkmcnt(0)
	v_mul_f32_e32 v37, v37, v65
	v_fmac_f32_e32 v37, v36, v64
	v_mul_f32_e32 v36, v39, v67
	v_fmac_f32_e32 v36, v38, v66
	v_add_f32_e32 v36, v37, v36
	v_add_f32_e32 v36, v40, v36
	v_add_f32_e32 v40, v44, v36
	ds_read_b128 v[36:39], v63 offset:224
	v_lshlrev_b32_e32 v41, 16, v32
	v_and_b32_e32 v32, 0xffff0000, v32
	v_lshlrev_b32_e32 v42, 16, v33
	v_and_b32_e32 v43, 0xffff0000, v33
	v_lshlrev_b32_e32 v44, 16, v34
	v_and_b32_e32 v45, 0xffff0000, v34
	v_lshlrev_b32_e32 v46, 16, v35
	v_and_b32_e32 v47, 0xffff0000, v35
	s_waitcnt lgkmcnt(0)
	v_mul_f32_e32 v37, v37, v32
	ds_read_b128 v[32:35], v63 offset:240
	v_fmac_f32_e32 v37, v36, v41
	v_mul_f32_e32 v36, v39, v43
	v_fmac_f32_e32 v36, v38, v42
	v_add_f32_e32 v36, v37, v36
	s_waitcnt lgkmcnt(0)
	v_mul_f32_e32 v33, v33, v45
	v_fmac_f32_e32 v33, v32, v44
	v_mul_f32_e32 v32, v35, v47
	v_fmac_f32_e32 v32, v34, v46
	v_add_f32_e32 v32, v33, v32
	v_add_f32_e32 v32, v36, v32
	v_add_f32_e32 v36, v40, v32
	ds_read_b128 v[32:35], v63 offset:256
	s_waitcnt vmcnt(4)
	v_lshlrev_b32_e32 v37, 16, v28
	v_and_b32_e32 v28, 0xffff0000, v28
	v_lshlrev_b32_e32 v38, 16, v29
	v_and_b32_e32 v39, 0xffff0000, v29
	v_lshlrev_b32_e32 v40, 16, v30
	v_and_b32_e32 v41, 0xffff0000, v30
	v_lshlrev_b32_e32 v42, 16, v31
	v_and_b32_e32 v43, 0xffff0000, v31
	s_waitcnt lgkmcnt(0)
	v_mul_f32_e32 v33, v33, v28
	ds_read_b128 v[28:31], v63 offset:272
	v_fmac_f32_e32 v33, v32, v37
	v_mul_f32_e32 v32, v35, v39
	v_fmac_f32_e32 v32, v34, v38
	v_add_f32_e32 v32, v33, v32
	s_waitcnt lgkmcnt(0)
	v_mul_f32_e32 v29, v29, v41
	v_fmac_f32_e32 v29, v28, v40
	v_mul_f32_e32 v28, v31, v43
	v_fmac_f32_e32 v28, v30, v42
	v_add_f32_e32 v28, v29, v28
	v_add_f32_e32 v28, v32, v28
	v_add_f32_e32 v32, v36, v28
	ds_read_b128 v[28:31], v63 offset:288
	v_lshlrev_b32_e32 v33, 16, v24
	v_and_b32_e32 v24, 0xffff0000, v24
	v_lshlrev_b32_e32 v34, 16, v25
	v_and_b32_e32 v35, 0xffff0000, v25
	v_lshlrev_b32_e32 v36, 16, v26
	v_and_b32_e32 v37, 0xffff0000, v26
	v_lshlrev_b32_e32 v38, 16, v27
	v_and_b32_e32 v39, 0xffff0000, v27
	s_waitcnt lgkmcnt(0)
	v_mul_f32_e32 v29, v29, v24
	ds_read_b128 v[24:27], v63 offset:304
	v_fmac_f32_e32 v29, v28, v33
	v_mul_f32_e32 v28, v31, v35
	v_fmac_f32_e32 v28, v30, v34
	v_add_f32_e32 v28, v29, v28
	s_waitcnt lgkmcnt(0)
	v_mul_f32_e32 v25, v25, v37
	v_fmac_f32_e32 v25, v24, v36
	v_mul_f32_e32 v24, v27, v39
	v_fmac_f32_e32 v24, v26, v38
	v_add_f32_e32 v24, v25, v24
	v_add_f32_e32 v24, v28, v24
	v_add_f32_e32 v28, v32, v24
	ds_read_b128 v[24:27], v63 offset:320
	v_lshlrev_b32_e32 v29, 16, v20
	v_and_b32_e32 v20, 0xffff0000, v20
	v_lshlrev_b32_e32 v30, 16, v21
	v_and_b32_e32 v31, 0xffff0000, v21
	v_lshlrev_b32_e32 v32, 16, v22
	v_and_b32_e32 v33, 0xffff0000, v22
	v_lshlrev_b32_e32 v34, 16, v23
	v_and_b32_e32 v35, 0xffff0000, v23
	s_waitcnt lgkmcnt(0)
	v_mul_f32_e32 v25, v25, v20
	ds_read_b128 v[20:23], v63 offset:336
	v_fmac_f32_e32 v25, v24, v29
	v_mul_f32_e32 v24, v27, v31
	v_fmac_f32_e32 v24, v26, v30
	v_add_f32_e32 v24, v25, v24
	s_waitcnt lgkmcnt(0)
	v_mul_f32_e32 v21, v21, v33
	v_fmac_f32_e32 v21, v20, v32
	v_mul_f32_e32 v20, v23, v35
	v_fmac_f32_e32 v20, v22, v34
	v_add_f32_e32 v20, v21, v20
	v_add_f32_e32 v20, v24, v20
	v_add_f32_e32 v24, v28, v20
	ds_read_b128 v[20:23], v63 offset:352
	v_lshlrev_b32_e32 v25, 16, v16
	v_and_b32_e32 v16, 0xffff0000, v16
	v_lshlrev_b32_e32 v26, 16, v17
	v_and_b32_e32 v27, 0xffff0000, v17
	v_lshlrev_b32_e32 v28, 16, v18
	v_and_b32_e32 v29, 0xffff0000, v18
	v_lshlrev_b32_e32 v30, 16, v19
	v_and_b32_e32 v31, 0xffff0000, v19
	s_waitcnt lgkmcnt(0)
	v_mul_f32_e32 v21, v21, v16
	ds_read_b128 v[16:19], v63 offset:368
	v_fmac_f32_e32 v21, v20, v25
	v_mul_f32_e32 v20, v23, v27
	v_fmac_f32_e32 v20, v22, v26
	v_add_f32_e32 v20, v21, v20
	s_waitcnt lgkmcnt(0)
	v_mul_f32_e32 v17, v17, v29
	v_fmac_f32_e32 v17, v16, v28
	v_mul_f32_e32 v16, v19, v31
	v_fmac_f32_e32 v16, v18, v30
	v_add_f32_e32 v16, v17, v16
	v_add_f32_e32 v16, v20, v16
	global_load_dwordx4 v[64:67], v[56:57], off offset:256
	v_add_f32_e32 v20, v24, v16
	ds_read_b128 v[16:19], v63 offset:384
	s_waitcnt vmcnt(1)
	v_lshlrev_b32_e32 v21, 16, v12
	v_and_b32_e32 v12, 0xffff0000, v12
	v_lshlrev_b32_e32 v22, 16, v13
	v_and_b32_e32 v23, 0xffff0000, v13
	v_lshlrev_b32_e32 v24, 16, v14
	v_and_b32_e32 v25, 0xffff0000, v14
	v_lshlrev_b32_e32 v26, 16, v15
	v_and_b32_e32 v27, 0xffff0000, v15
	s_waitcnt lgkmcnt(0)
	v_mul_f32_e32 v17, v17, v12
	ds_read_b128 v[12:15], v63 offset:400
	v_fmac_f32_e32 v17, v16, v21
	v_mul_f32_e32 v16, v19, v23
	global_load_dwordx4 v[68:71], v[56:57], off offset:272
	v_fmac_f32_e32 v16, v18, v22
	s_waitcnt lgkmcnt(0)
; #define LAS __attribute__((address_space(3)))
; __device__ __forceinline__ float dot4(f32x4 a, f32x4 b) { return (a[0] * b[0] + a[1] * b[1]) + (a[2] * b[2] + a[3] * b[3]); }
; __device__ __forceinline__ void unpack8(u32x4 w, f32x4& a, f32x4& b) { a = (f32x4){bflo(w.x), bfhi(w.x), bflo(w.y), bfhi(w.y)}; b = (f32x4){bflo(w.z), bfhi(w.z), bflo(w.w), bfhi(w.w)}; }
; __device__ __forceinline__ void sample_mix_even(Frame& F0, int j, int b) {
;     ...
;         for (int hb = 0; hb < 2; ++hb) {
;             u32x4 pr[16];
; #pragma unroll
;             for (int i = 0; i < 16; ++i) pr[i] = *(const u32x4*)(pm + hb * 128 + i * 8);
; #pragma unroll
;             for (int i = 0; i < 16; ++i) { f32x4 p0, p1; unpack8(pr[i], p0, p1); const LAS float* q = pg + hb * 128 + i * 8; a += dot4(p0, *(const LAS f32x4*)q) + dot4(p1, *(const LAS f32x4*)(q + 4)); }
	v_mul_f32_e32 v13, v13, v25
	v_fmac_f32_e32 v13, v12, v24
	v_mul_f32_e32 v12, v15, v27
	v_fmac_f32_e32 v12, v14, v26
	v_add_f32_e32 v16, v17, v16
	v_add_f32_e32 v12, v13, v12
	v_add_f32_e32 v12, v16, v12
	v_add_f32_e32 v16, v20, v12
	ds_read_b128 v[12:15], v63 offset:416
	v_lshlrev_b32_e32 v17, 16, v8
	v_and_b32_e32 v8, 0xffff0000, v8
	v_lshlrev_b32_e32 v18, 16, v9
	v_and_b32_e32 v19, 0xffff0000, v9
	v_lshlrev_b32_e32 v20, 16, v10
	v_and_b32_e32 v21, 0xffff0000, v10
	v_lshlrev_b32_e32 v22, 16, v11
	v_and_b32_e32 v23, 0xffff0000, v11
	s_waitcnt lgkmcnt(0)
	v_mul_f32_e32 v13, v13, v8
	ds_read_b128 v[8:11], v63 offset:432
	global_load_dwordx4 v[72:75], v[56:57], off offset:288
	v_fmac_f32_e32 v13, v12, v17
	v_mul_f32_e32 v12, v15, v19
	v_fmac_f32_e32 v12, v14, v18
	s_waitcnt lgkmcnt(0)
	v_mul_f32_e32 v9, v9, v21
	v_fmac_f32_e32 v9, v8, v20
	v_mul_f32_e32 v8, v11, v23
	v_fmac_f32_e32 v8, v10, v22
	v_add_f32_e32 v12, v13, v12
	v_add_f32_e32 v8, v9, v8
	v_add_f32_e32 v8, v12, v8
	v_add_f32_e32 v12, v16, v8
	ds_read_b128 v[8:11], v63 offset:448
	v_lshlrev_b32_e32 v13, 16, v4
	v_and_b32_e32 v4, 0xffff0000, v4
	v_lshlrev_b32_e32 v14, 16, v5
	v_and_b32_e32 v15, 0xffff0000, v5
	v_lshlrev_b32_e32 v16, 16, v6
	v_and_b32_e32 v17, 0xffff0000, v6
	v_lshlrev_b32_e32 v18, 16, v7
	v_and_b32_e32 v19, 0xffff0000, v7
	s_waitcnt lgkmcnt(0)
	v_mul_f32_e32 v9, v9, v4
	ds_read_b128 v[4:7], v63 offset:464
	global_load_dwordx4 v[44:47], v[56:57], off offset:304
	v_fmac_f32_e32 v9, v8, v13
	v_mul_f32_e32 v8, v11, v15
	v_fmac_f32_e32 v8, v10, v14
	s_waitcnt lgkmcnt(0)
	v_mul_f32_e32 v5, v5, v17
	v_fmac_f32_e32 v5, v4, v16
	v_mul_f32_e32 v4, v7, v19
	v_fmac_f32_e32 v4, v6, v18
	v_add_f32_e32 v8, v9, v8
	v_add_f32_e32 v4, v5, v4
	v_add_f32_e32 v4, v8, v4
	v_add_f32_e32 v8, v12, v4
	ds_read_b128 v[4:7], v63 offset:480
	v_lshlrev_b32_e32 v9, 16, v0
	v_and_b32_e32 v0, 0xffff0000, v0
	v_lshlrev_b32_e32 v10, 16, v1
	v_and_b32_e32 v11, 0xffff0000, v1
	v_lshlrev_b32_e32 v12, 16, v2
	v_and_b32_e32 v13, 0xffff0000, v2
	v_lshlrev_b32_e32 v14, 16, v3
	v_and_b32_e32 v15, 0xffff0000, v3
	s_waitcnt lgkmcnt(0)
	v_mul_f32_e32 v5, v5, v0
	ds_read_b128 v[0:3], v63 offset:496
	v_fmac_f32_e32 v5, v4, v9
	v_mul_f32_e32 v4, v7, v11
	v_fmac_f32_e32 v4, v6, v10
	v_add_f32_e32 v4, v5, v4
	s_waitcnt lgkmcnt(0)
	v_mul_f32_e32 v1, v1, v13
	v_fmac_f32_e32 v1, v0, v12
	v_mul_f32_e32 v0, v3, v15
	v_fmac_f32_e32 v0, v2, v14
	v_add_f32_e32 v0, v1, v0
	v_add_f32_e32 v0, v4, v0
	v_add_f32_e32 v84, v8, v0
	global_load_dwordx4 v[32:35], v[56:57], off offset:368
	global_load_dwordx4 v[36:39], v[56:57], off offset:352
	global_load_dwordx4 v[40:43], v[56:57], off offset:336
	global_load_dwordx4 v[76:79], v[56:57], off offset:320
	global_load_dwordx4 v[16:19], v[56:57], off offset:432
	global_load_dwordx4 v[20:23], v[56:57], off offset:416
	global_load_dwordx4 v[24:27], v[56:57], off offset:400
	global_load_dwordx4 v[28:31], v[56:57], off offset:384
	global_load_dwordx4 v[0:3], v[56:57], off offset:496
	global_load_dwordx4 v[4:7], v[56:57], off offset:480
	global_load_dwordx4 v[8:11], v[56:57], off offset:464
	global_load_dwordx4 v[12:15], v[56:57], off offset:448
	ds_read_b128 v[80:83], v63 offset:512
	s_waitcnt vmcnt(15)
	v_lshlrev_b32_e32 v56, 16, v64
	v_and_b32_e32 v57, 0xffff0000, v64
	v_lshlrev_b32_e32 v85, 16, v65
	v_and_b32_e32 v86, 0xffff0000, v65
	v_lshlrev_b32_e32 v87, 16, v66
	v_and_b32_e32 v88, 0xffff0000, v66
	v_lshlrev_b32_e32 v89, 16, v67
	v_and_b32_e32 v90, 0xffff0000, v67
	ds_read_b128 v[64:67], v63 offset:528
	s_waitcnt lgkmcnt(1)
	v_mul_f32_e32 v57, v81, v57
	v_fmac_f32_e32 v57, v80, v56
	v_mul_f32_e32 v56, v83, v86
	v_fmac_f32_e32 v56, v82, v85
	v_add_f32_e32 v56, v57, v56
	s_waitcnt lgkmcnt(0)
	v_mul_f32_e32 v57, v65, v88
	v_fmac_f32_e32 v57, v64, v87
	v_mul_f32_e32 v64, v67, v90
	v_fmac_f32_e32 v64, v66, v89
	v_add_f32_e32 v57, v57, v64
	ds_read_b128 v[64:67], v63 offset:544
	v_add_f32_e32 v56, v56, v57
	s_waitcnt vmcnt(14)
	v_lshlrev_b32_e32 v57, 16, v68
	v_and_b32_e32 v68, 0xffff0000, v68
	v_add_f32_e32 v56, v84, v56
	v_lshlrev_b32_e32 v80, 16, v69
	v_and_b32_e32 v81, 0xffff0000, v69
	v_lshlrev_b32_e32 v82, 16, v70
	v_and_b32_e32 v83, 0xffff0000, v70
	v_lshlrev_b32_e32 v84, 16, v71
	v_and_b32_e32 v85, 0xffff0000, v71
	s_waitcnt lgkmcnt(0)
	v_mul_f32_e32 v65, v65, v68
	ds_read_b128 v[68:71], v63 offset:560
	v_fmac_f32_e32 v65, v64, v57
	v_mul_f32_e32 v57, v67, v81
	v_fmac_f32_e32 v57, v66, v80
	v_add_f32_e32 v57, v65, v57
	s_waitcnt lgkmcnt(0)
	v_mul_f32_e32 v64, v69, v83
	v_mul_f32_e32 v65, v71, v85
	v_fmac_f32_e32 v64, v68, v82
	v_fmac_f32_e32 v65, v70, v84
	v_add_f32_e32 v64, v64, v65
	v_add_f32_e32 v57, v57, v64
	ds_read_b128 v[64:67], v63 offset:576
	s_waitcnt vmcnt(13)
	v_and_b32_e32 v68, 0xffff0000, v72
	v_add_f32_e32 v56, v56, v57
	v_lshlrev_b32_e32 v57, 16, v72
	v_lshlrev_b32_e32 v72, 16, v73
	s_waitcnt lgkmcnt(0)
	v_mul_f32_e32 v65, v65, v68
	ds_read_b128 v[68:71], v63 offset:592
	v_and_b32_e32 v73, 0xffff0000, v73
	v_fmac_f32_e32 v65, v64, v57
	v_mul_f32_e32 v57, v67, v73
	v_lshlrev_b32_e32 v80, 16, v74
	v_and_b32_e32 v74, 0xffff0000, v74
	v_lshlrev_b32_e32 v81, 16, v75
	v_and_b32_e32 v75, 0xffff0000, v75
	v_fmac_f32_e32 v57, v66, v72
	v_add_f32_e32 v57, v65, v57
	s_waitcnt lgkmcnt(0)
	v_mul_f32_e32 v64, v69, v74
	v_mul_f32_e32 v65, v71, v75
	v_fmac_f32_e32 v64, v68, v80
	v_fmac_f32_e32 v65, v70, v81
	v_add_f32_e32 v64, v64, v65
	v_add_f32_e32 v57, v57, v64
	ds_read_b128 v[64:67], v63 offset:608
	v_add_f32_e32 v56, v56, v57
	s_waitcnt vmcnt(12)
; #define LAS __attribute__((address_space(3)))
; __device__ __forceinline__ float silu_f(float x) { return x * __builtin_amdgcn_rcpf(1.f + __builtin_amdgcn_exp2f(-1.4426950408889634f * x)); }
; __device__ __forceinline__ float dot4(f32x4 a, f32x4 b) { return (a[0] * b[0] + a[1] * b[1]) + (a[2] * b[2] + a[3] * b[3]); }
; __device__ __forceinline__ void unpack8(u32x4 w, f32x4& a, f32x4& b) { a = (f32x4){bflo(w.x), bfhi(w.x), bflo(w.y), bfhi(w.y)}; b = (f32x4){bflo(w.z), bfhi(w.z), bflo(w.w), bfhi(w.w)}; }
; __device__ __forceinline__ void sample_mix_even(Frame& F0, int j, int b) {
;     ...
;         for (int hb = 0; hb < 2; ++hb) {
;             u32x4 pr[16];
; #pragma unroll
;             for (int i = 0; i < 16; ++i) pr[i] = *(const u32x4*)(pm + hb * 128 + i * 8);
; #pragma unroll
;             for (int i = 0; i < 16; ++i) { f32x4 p0, p1; unpack8(pr[i], p0, p1); const LAS float* q = pg + hb * 128 + i * 8; a += dot4(p0, *(const LAS f32x4*)q) + dot4(p1, *(const LAS f32x4*)(q + 4)); }
;         }
;         const float ya = a * FIN(12)[j * 1024 + d] * silu_f(z[1024 + d]);
;         const float vn = vv[k] * rv * FIN(15)[j * 1024 + d];
	v_lshlrev_b32_e32 v57, 16, v44
	v_and_b32_e32 v44, 0xffff0000, v44
	v_lshlrev_b32_e32 v68, 16, v45
	v_and_b32_e32 v69, 0xffff0000, v45
	v_lshlrev_b32_e32 v70, 16, v46
	v_and_b32_e32 v71, 0xffff0000, v46
	v_lshlrev_b32_e32 v72, 16, v47
	v_and_b32_e32 v73, 0xffff0000, v47
	s_waitcnt lgkmcnt(0)
	v_mul_f32_e32 v65, v65, v44
	ds_read_b128 v[44:47], v63 offset:624
	v_fmac_f32_e32 v65, v64, v57
	v_mul_f32_e32 v57, v67, v69
	v_fmac_f32_e32 v57, v66, v68
	v_add_f32_e32 v57, v65, v57
	s_waitcnt lgkmcnt(0)
	v_mul_f32_e32 v45, v45, v71
	v_fmac_f32_e32 v45, v44, v70
	v_mul_f32_e32 v44, v47, v73
	v_fmac_f32_e32 v44, v46, v72
	v_add_f32_e32 v44, v45, v44
	v_add_f32_e32 v44, v57, v44
	v_add_f32_e32 v56, v56, v44
	ds_read_b128 v[44:47], v63 offset:640
	s_waitcnt vmcnt(8)
	v_and_b32_e32 v64, 0xffff0000, v76
	v_lshlrev_b32_e32 v57, 16, v76
	v_and_b32_e32 v69, 0xffff0000, v77
	v_lshlrev_b32_e32 v68, 16, v77
	s_waitcnt lgkmcnt(0)
	v_mul_f32_e32 v45, v45, v64
	ds_read_b128 v[64:67], v63 offset:656
	v_fmac_f32_e32 v45, v44, v57
	v_mul_f32_e32 v44, v47, v69
	v_and_b32_e32 v71, 0xffff0000, v78
	v_and_b32_e32 v73, 0xffff0000, v79
	v_fmac_f32_e32 v44, v46, v68
	v_lshlrev_b32_e32 v70, 16, v78
	v_lshlrev_b32_e32 v72, 16, v79
	v_add_f32_e32 v44, v45, v44
	s_waitcnt lgkmcnt(0)
	v_mul_f32_e32 v45, v65, v71
	v_mul_f32_e32 v46, v67, v73
	v_fmac_f32_e32 v45, v64, v70
	v_fmac_f32_e32 v46, v66, v72
	v_add_f32_e32 v45, v45, v46
	v_add_f32_e32 v44, v44, v45
	v_add_f32_e32 v56, v56, v44
	ds_read_b128 v[44:47], v63 offset:672
	v_lshlrev_b32_e32 v57, 16, v40
	v_and_b32_e32 v40, 0xffff0000, v40
	v_lshlrev_b32_e32 v64, 16, v41
	v_and_b32_e32 v65, 0xffff0000, v41
	v_lshlrev_b32_e32 v66, 16, v42
	v_and_b32_e32 v67, 0xffff0000, v42
	v_lshlrev_b32_e32 v68, 16, v43
	v_and_b32_e32 v69, 0xffff0000, v43
	s_waitcnt lgkmcnt(0)
	v_mul_f32_e32 v45, v45, v40
	ds_read_b128 v[40:43], v63 offset:688
	v_fmac_f32_e32 v45, v44, v57
	v_mul_f32_e32 v44, v47, v65
	v_fmac_f32_e32 v44, v46, v64
	v_add_f32_e32 v44, v45, v44
	s_waitcnt lgkmcnt(0)
	v_mul_f32_e32 v41, v41, v67
	v_fmac_f32_e32 v41, v40, v66
	v_mul_f32_e32 v40, v43, v69
	v_fmac_f32_e32 v40, v42, v68
	v_add_f32_e32 v40, v41, v40
	v_add_f32_e32 v40, v44, v40
	v_add_f32_e32 v44, v56, v40
	ds_read_b128 v[40:43], v63 offset:704
	v_lshlrev_b32_e32 v45, 16, v36
	v_and_b32_e32 v36, 0xffff0000, v36
	v_lshlrev_b32_e32 v46, 16, v37
	v_and_b32_e32 v47, 0xffff0000, v37
	v_lshlrev_b32_e32 v56, 16, v38
	v_and_b32_e32 v57, 0xffff0000, v38
	v_lshlrev_b32_e32 v64, 16, v39
	v_and_b32_e32 v65, 0xffff0000, v39
	s_waitcnt lgkmcnt(0)
	v_mul_f32_e32 v41, v41, v36
	ds_read_b128 v[36:39], v63 offset:720
	v_fmac_f32_e32 v41, v40, v45
	v_mul_f32_e32 v40, v43, v47
	v_fmac_f32_e32 v40, v42, v46
	v_add_f32_e32 v40, v41, v40
	s_waitcnt lgkmcnt(0)
	v_mul_f32_e32 v37, v37, v57
	v_fmac_f32_e32 v37, v36, v56
	v_mul_f32_e32 v36, v39, v65
	v_fmac_f32_e32 v36, v38, v64
	v_add_f32_e32 v36, v37, v36
	v_add_f32_e32 v36, v40, v36
	v_add_f32_e32 v40, v44, v36
	ds_read_b128 v[36:39], v63 offset:736
	v_lshlrev_b32_e32 v41, 16, v32
	v_and_b32_e32 v32, 0xffff0000, v32
	v_lshlrev_b32_e32 v42, 16, v33
	v_and_b32_e32 v43, 0xffff0000, v33
	v_lshlrev_b32_e32 v44, 16, v34
	v_and_b32_e32 v45, 0xffff0000, v34
	v_lshlrev_b32_e32 v46, 16, v35
	v_and_b32_e32 v47, 0xffff0000, v35
	s_waitcnt lgkmcnt(0)
	v_mul_f32_e32 v37, v37, v32
	ds_read_b128 v[32:35], v63 offset:752
	v_fmac_f32_e32 v37, v36, v41
	v_mul_f32_e32 v36, v39, v43
	v_fmac_f32_e32 v36, v38, v42
	v_add_f32_e32 v36, v37, v36
	s_waitcnt lgkmcnt(0)
	v_mul_f32_e32 v33, v33, v45
	v_fmac_f32_e32 v33, v32, v44
	v_mul_f32_e32 v32, v35, v47
	v_fmac_f32_e32 v32, v34, v46
	v_add_f32_e32 v32, v33, v32
	v_add_f32_e32 v32, v36, v32
	v_add_f32_e32 v36, v40, v32
	ds_read_b128 v[32:35], v63 offset:768
	s_waitcnt vmcnt(4)
	v_lshlrev_b32_e32 v37, 16, v28
	v_and_b32_e32 v28, 0xffff0000, v28
	v_lshlrev_b32_e32 v38, 16, v29
	v_and_b32_e32 v39, 0xffff0000, v29
	v_lshlrev_b32_e32 v40, 16, v30
	v_and_b32_e32 v41, 0xffff0000, v30
	v_lshlrev_b32_e32 v42, 16, v31
	v_and_b32_e32 v43, 0xffff0000, v31
	s_waitcnt lgkmcnt(0)
	v_mul_f32_e32 v33, v33, v28
	ds_read_b128 v[28:31], v63 offset:784
	v_fmac_f32_e32 v33, v32, v37
	v_mul_f32_e32 v32, v35, v39
	v_fmac_f32_e32 v32, v34, v38
	v_add_f32_e32 v32, v33, v32
	s_waitcnt lgkmcnt(0)
	v_mul_f32_e32 v29, v29, v41
	v_fmac_f32_e32 v29, v28, v40
	v_mul_f32_e32 v28, v31, v43
	v_fmac_f32_e32 v28, v30, v42
	v_add_f32_e32 v28, v29, v28
	v_add_f32_e32 v28, v32, v28
	v_add_f32_e32 v32, v36, v28
	ds_read_b128 v[28:31], v63 offset:800
	v_lshlrev_b32_e32 v33, 16, v24
	v_and_b32_e32 v24, 0xffff0000, v24
	v_lshlrev_b32_e32 v34, 16, v25
	v_and_b32_e32 v25, 0xffff0000, v25
	s_waitcnt lgkmcnt(0)
	v_mul_f32_e32 v24, v29, v24
	v_fmac_f32_e32 v24, v28, v33
	v_add_u32_e32 v28, s90, v48
	v_mul_f32_e32 v25, v31, v25
	v_ashrrev_i32_e32 v29, 31, v28
	v_fmac_f32_e32 v25, v30, v34
	v_lshlrev_b64 v[30:31], 2, v[28:29]
	v_lshl_add_u64 v[28:29], s[10:11], 0, v[30:31]
	global_load_dword v34, v[28:29], off
	v_lshlrev_b32_e32 v35, 16, v26
	v_and_b32_e32 v36, 0xffff0000, v26
	v_lshlrev_b32_e32 v37, 16, v27
	v_and_b32_e32 v38, 0xffff0000, v27
	v_add_f32_e32 v33, v24, v25
	ds_read_b128 v[24:27], v63 offset:816
	v_lshlrev_b32_e32 v39, 16, v23
	v_and_b32_e32 v40, 0xffff0000, v23
	v_lshl_add_u64 v[30:31], s[4:5], 0, v[30:31]
	s_waitcnt lgkmcnt(0)
	v_mul_f32_e32 v25, v25, v36
	v_fmac_f32_e32 v25, v24, v35
	v_mul_f32_e32 v24, v27, v38
	v_fmac_f32_e32 v24, v26, v37
	v_add_f32_e32 v24, v25, v24
	v_add_f32_e32 v24, v33, v24
	v_add_f32_e32 v32, v32, v24
	ds_read_b128 v[24:27], v63 offset:832
	v_lshlrev_b32_e32 v33, 16, v20
	v_and_b32_e32 v20, 0xffff0000, v20
	v_lshlrev_b32_e32 v35, 16, v21
	v_and_b32_e32 v36, 0xffff0000, v21
	v_lshlrev_b32_e32 v37, 16, v22
	v_and_b32_e32 v38, 0xffff0000, v22
	s_waitcnt lgkmcnt(0)
; #define LAS __attribute__((address_space(3)))
; __device__ __forceinline__ float silu_f(float x) { return x * __builtin_amdgcn_rcpf(1.f + __builtin_amdgcn_exp2f(-1.4426950408889634f * x)); }
; __device__ __forceinline__ float dot4(f32x4 a, f32x4 b) { return (a[0] * b[0] + a[1] * b[1]) + (a[2] * b[2] + a[3] * b[3]); }
; __device__ __forceinline__ void unpack8(u32x4 w, f32x4& a, f32x4& b) { a = (f32x4){bflo(w.x), bfhi(w.x), bflo(w.y), bfhi(w.y)}; b = (f32x4){bflo(w.z), bfhi(w.z), bflo(w.w), bfhi(w.w)}; }
; __device__ __forceinline__ void sample_mix_even(Frame& F0, int j, int b) {
;     ...
;             for (int i = 0; i < 16; ++i) { f32x4 p0, p1; unpack8(pr[i], p0, p1); const LAS float* q = pg + hb * 128 + i * 8; a += dot4(p0, *(const LAS f32x4*)q) + dot4(p1, *(const LAS f32x4*)(q + 4)); }
;         }
;         const float ya = a * FIN(12)[j * 1024 + d] * silu_f(z[1024 + d]);
;         const float vn = vv[k] * rv * FIN(15)[j * 1024 + d];
;         F.out[O_SGUV + (size_t)(j * 128 + b) * 1024 + d] = vn;
;         const float mixed = FIN(13)[(size_t)(j * 4 + g) * 16384] * vn + FIN(14)[(j * 4 + g) * 128];
	v_mul_f32_e32 v25, v25, v20
	ds_read_b128 v[20:23], v63 offset:848
	v_fmac_f32_e32 v25, v24, v33
	v_mul_f32_e32 v24, v27, v36
	v_fmac_f32_e32 v24, v26, v35
	v_add_f32_e32 v24, v25, v24
	s_waitcnt lgkmcnt(0)
	v_mul_f32_e32 v21, v21, v38
	v_fmac_f32_e32 v21, v20, v37
	v_mul_f32_e32 v20, v23, v40
	v_fmac_f32_e32 v20, v22, v39
	v_add_f32_e32 v20, v21, v20
	v_add_f32_e32 v20, v24, v20
	v_add_f32_e32 v24, v32, v20
	ds_read_b128 v[20:23], v63 offset:864
	v_lshlrev_b32_e32 v25, 16, v16
	v_and_b32_e32 v16, 0xffff0000, v16
	v_lshlrev_b32_e32 v26, 16, v17
	v_and_b32_e32 v27, 0xffff0000, v17
	v_lshlrev_b32_e32 v32, 16, v18
	v_and_b32_e32 v33, 0xffff0000, v18
	v_lshlrev_b32_e32 v35, 16, v19
	v_and_b32_e32 v36, 0xffff0000, v19
	s_waitcnt lgkmcnt(0)
	v_mul_f32_e32 v21, v21, v16
	ds_read_b128 v[16:19], v63 offset:880
	v_fmac_f32_e32 v21, v20, v25
	v_mul_f32_e32 v20, v23, v27
	v_fmac_f32_e32 v20, v22, v26
	v_add_f32_e32 v20, v21, v20
	s_waitcnt lgkmcnt(0)
	v_mul_f32_e32 v17, v17, v33
	v_fmac_f32_e32 v17, v16, v32
	v_mul_f32_e32 v16, v19, v36
	v_fmac_f32_e32 v16, v18, v35
	v_add_f32_e32 v16, v17, v16
	v_add_f32_e32 v16, v20, v16
	v_add_f32_e32 v20, v24, v16
	ds_read_b128 v[16:19], v63 offset:896
	s_waitcnt vmcnt(1)
	v_lshlrev_b32_e32 v21, 16, v12
	v_and_b32_e32 v12, 0xffff0000, v12
	v_lshlrev_b32_e32 v22, 16, v13
	v_and_b32_e32 v23, 0xffff0000, v13
	v_lshlrev_b32_e32 v24, 16, v14
	v_and_b32_e32 v25, 0xffff0000, v14
	v_lshlrev_b32_e32 v26, 16, v15
	v_and_b32_e32 v27, 0xffff0000, v15
	s_waitcnt lgkmcnt(0)
	v_mul_f32_e32 v17, v17, v12
	ds_read_b128 v[12:15], v63 offset:912
	v_fmac_f32_e32 v17, v16, v21
	v_mul_f32_e32 v16, v19, v23
	v_fmac_f32_e32 v16, v18, v22
	v_add_f32_e32 v18, v17, v16
	s_waitcnt lgkmcnt(0)
	v_mul_f32_e32 v13, v13, v25
	v_fmac_f32_e32 v13, v12, v24
	v_mul_f32_e32 v12, v15, v27
	v_fmac_f32_e32 v12, v14, v26
	v_add_f32_e32 v19, v13, v12
	v_add_co_u32_e32 v14, vcc, s70, v50
	v_mul_f32_e32 v12, v60, v59
	s_nop 0
	v_addc_co_u32_e32 v15, vcc, 0, v51, vcc
	s_waitcnt vmcnt(0)
	v_mul_f32_e32 v23, v12, v34
	v_lshl_add_u64 v[12:13], v[48:49], 2, s[2:3]
	s_mov_b32 s2, 0x54b0000
	v_add_co_u32_e32 v16, vcc, s2, v12
	global_load_dword v21, v[30:31], off
	s_nop 0
	v_addc_co_u32_e32 v17, vcc, 0, v13, vcc
	global_load_dword v22, v[14:15], off offset:-4096
	v_add_f32_e32 v18, v18, v19
	global_store_dword v[16:17], v23, off
	v_add_co_u32_e32 v16, vcc, s94, v50
	v_add_f32_e32 v18, v20, v18
	s_nop 0
	v_addc_co_u32_e32 v17, vcc, 0, v51, vcc
	global_load_dword v24, v[16:17], off
	v_lshlrev_b64 v[16:17], 16, v[54:55]
	v_lshl_add_u64 v[16:17], s[6:7], 0, v[16:17]
	global_load_dword v19, v[16:17], off
	v_lshlrev_b32_e32 v16, 7, v54
	v_ashrrev_i32_e32 v17, 31, v16
	v_lshl_add_u64 v[16:17], v[16:17], 2, s[8:9]
	global_load_dword v25, v[16:17], off
	global_load_dword v26, v[14:15], off
	ds_read_b128 v[14:17], v63 offset:928
	v_lshlrev_b32_e32 v20, 16, v8
	v_and_b32_e32 v8, 0xffff0000, v8
	v_lshlrev_b32_e32 v27, 16, v9
	v_and_b32_e32 v32, 0xffff0000, v9
	v_lshlrev_b32_e32 v33, 16, v10
	v_and_b32_e32 v34, 0xffff0000, v10
	v_lshlrev_b32_e32 v35, 16, v11
	v_and_b32_e32 v36, 0xffff0000, v11
	s_waitcnt lgkmcnt(0)
	v_mul_f32_e32 v15, v15, v8
	ds_read_b128 v[8:11], v63 offset:944
	v_fmac_f32_e32 v15, v14, v20
	v_mul_f32_e32 v14, v17, v32
	v_fmac_f32_e32 v14, v16, v27
	v_add_f32_e32 v14, v15, v14
	s_waitcnt lgkmcnt(0)
	v_mul_f32_e32 v9, v9, v34
	v_fmac_f32_e32 v9, v8, v33
	v_mul_f32_e32 v8, v11, v36
	v_fmac_f32_e32 v8, v10, v35
	v_add_f32_e32 v8, v9, v8
	v_add_f32_e32 v8, v14, v8
	v_add_f32_e32 v14, v18, v8
	ds_read_b128 v[8:11], v63 offset:960
	v_lshlrev_b32_e32 v15, 16, v4
	v_and_b32_e32 v4, 0xffff0000, v4
	v_lshlrev_b32_e32 v16, 16, v5
	v_and_b32_e32 v17, 0xffff0000, v5
	v_lshlrev_b32_e32 v18, 16, v6
	v_and_b32_e32 v20, 0xffff0000, v6
	v_lshlrev_b32_e32 v27, 16, v7
	v_and_b32_e32 v32, 0xffff0000, v7
	s_waitcnt lgkmcnt(0)
; __device__ __forceinline__ unsigned cvt_pk_bf16(float lo, float hi) { const f32x2cv v = {lo, hi}; return __builtin_bit_cast(unsigned, __builtin_convertvector(v, bf16x2cv)); }
; #define LAS __attribute__((address_space(3)))
; __device__ __forceinline__ float silu_f(float x) { return x * __builtin_amdgcn_rcpf(1.f + __builtin_amdgcn_exp2f(-1.4426950408889634f * x)); }
; __device__ __forceinline__ float dot4(f32x4 a, f32x4 b) { return (a[0] * b[0] + a[1] * b[1]) + (a[2] * b[2] + a[3] * b[3]); }
; __device__ __forceinline__ void unpack8(u32x4 w, f32x4& a, f32x4& b) { a = (f32x4){bflo(w.x), bfhi(w.x), bflo(w.y), bfhi(w.y)}; b = (f32x4){bflo(w.z), bfhi(w.z), bflo(w.w), bfhi(w.w)}; }
; __device__ __forceinline__ void sample_mix_even(Frame& F0, int j, int b) {
;     ...
;             for (int i = 0; i < 16; ++i) { f32x4 p0, p1; unpack8(pr[i], p0, p1); const LAS float* q = pg + hb * 128 + i * 8; a += dot4(p0, *(const LAS f32x4*)q) + dot4(p1, *(const LAS f32x4*)(q + 4)); }
;         }
;         const float ya = a * FIN(12)[j * 1024 + d] * silu_f(z[1024 + d]);
;         const float vn = vv[k] * rv * FIN(15)[j * 1024 + d];
;         F.out[O_SGUV + (size_t)(j * 128 + b) * 1024 + d] = vn;
;         const float mixed = FIN(13)[(size_t)(j * 4 + g) * 16384] * vn + FIN(14)[(j * 4 + g) * 128];
;         const float yb = z[2048 + d] * mixed * silu_f(z[4096 + d]);
;         ((bf16_t*)(F.ws + WS_SA2))[(size_t)b * 2048 + d] = (bf16_t)(cvt_pk_bf16(ya, 0.f) & 0xffffu); ((bf16_t*)(F.ws + WS_SA2))[(size_t)b * 2048 + 1024 + d] = (bf16_t)(cvt_pk_bf16(yb, 0.f) & 0xffffu);
;     }
;     __syncthreads();
	v_mul_f32_e32 v9, v9, v4
	ds_read_b128 v[4:7], v63 offset:976
	v_fmac_f32_e32 v9, v8, v15
	v_mul_f32_e32 v8, v11, v17
	v_fmac_f32_e32 v8, v10, v16
	v_add_f32_e32 v8, v9, v8
	s_waitcnt lgkmcnt(0)
	v_mul_f32_e32 v5, v5, v20
	v_fmac_f32_e32 v5, v4, v18
	v_mul_f32_e32 v4, v7, v32
	v_fmac_f32_e32 v4, v6, v27
	v_add_f32_e32 v4, v5, v4
	v_add_f32_e32 v4, v8, v4
	v_add_f32_e32 v8, v14, v4
	ds_read_b128 v[4:7], v63 offset:992
	v_lshlrev_b32_e32 v9, 16, v0
	v_and_b32_e32 v0, 0xffff0000, v0
	v_lshlrev_b32_e32 v10, 16, v1
	v_and_b32_e32 v11, 0xffff0000, v1
	v_lshlrev_b32_e32 v14, 16, v2
	v_and_b32_e32 v15, 0xffff0000, v2
	v_lshlrev_b32_e32 v16, 16, v3
	v_and_b32_e32 v17, 0xffff0000, v3
	s_waitcnt lgkmcnt(0)
	v_mul_f32_e32 v5, v5, v0
	ds_read_b128 v[0:3], v63 offset:1008
	v_fmac_f32_e32 v5, v4, v9
	v_mul_f32_e32 v4, v7, v11
	v_fmac_f32_e32 v4, v6, v10
	v_add_f32_e32 v4, v5, v4
	s_waitcnt lgkmcnt(0)
	v_mul_f32_e32 v1, v1, v15
	v_fmac_f32_e32 v1, v0, v14
	v_mul_f32_e32 v0, v3, v17
	v_fmac_f32_e32 v0, v2, v16
	v_add_f32_e32 v0, v1, v0
	s_waitcnt vmcnt(5)
	v_mul_f32_e32 v3, 0xbfb8aa3b, v22
	v_exp_f32_e32 v3, v3
	v_add_f32_e32 v0, v4, v0
	v_add_f32_e32 v0, v8, v0
	v_mul_f32_e32 v0, v21, v0
	v_add_f32_e32 v1, 1.0, v3
	v_rcp_f32_e32 v1, v1
	s_waitcnt vmcnt(3)
	v_mul_f32_e32 v2, 0xbfb8aa3b, v24
	v_exp_f32_e32 v2, v2
	v_mul_f32_e32 v1, v22, v1
	v_mul_f32_e32 v0, v0, v1
	v_cvt_pk_bf16_f32 v3, v0, s0
	v_add_f32_e32 v2, 1.0, v2
	v_rcp_f32_e32 v2, v2
	s_waitcnt vmcnt(1)
	v_fmac_f32_e32 v25, v23, v19
	s_waitcnt vmcnt(0)
	v_mul_f32_e32 v1, v26, v25
	v_mul_f32_e32 v2, v24, v2
	v_mul_f32_e32 v2, v1, v2
	v_lshl_add_u64 v[0:1], v[48:49], 1, s[0:1]
	s_mov_b64 s[0:1], 0x1b500000
	v_lshl_add_u64 v[20:21], v[0:1], 0, s[0:1]
	s_mov_b32 s0, 0x1b500000
	v_add_co_u32_e32 v0, vcc, s0, v0
	s_nop 0
	s_nop 0
	v_addc_co_u32_e32 v1, vcc, 0, v1, vcc
	global_store_short v[0:1], v3, off
	v_cvt_pk_bf16_f32 v0, v2, s0
	global_store_short v[20:21], v0, off offset:2048
	s_mov_b64 s[0:1], 0x800
	s_mov_b64 s[0:1], 0x54b0000
	s_waitcnt vmcnt(0)
	s_waitcnt lgkmcnt(0)
	s_waitcnt lgkmcnt(0)
	s_waitcnt vmcnt(0)
	s_waitcnt lgkmcnt(0)
	s_waitcnt lgkmcnt(0)
	s_waitcnt vmcnt(0)
	s_waitcnt lgkmcnt(0)
	s_waitcnt lgkmcnt(0)
	s_waitcnt vmcnt(0)
	s_waitcnt lgkmcnt(0)
	s_waitcnt lgkmcnt(0)
	s_waitcnt vmcnt(0)
	s_waitcnt lgkmcnt(0)
	s_waitcnt lgkmcnt(0)
	s_waitcnt lgkmcnt(0)
	s_waitcnt lgkmcnt(0)
	s_waitcnt lgkmcnt(0)
	s_waitcnt lgkmcnt(0)
	s_waitcnt lgkmcnt(0)
	s_waitcnt lgkmcnt(0)
	s_waitcnt vmcnt(0)
	s_waitcnt lgkmcnt(0)
	s_waitcnt lgkmcnt(0)
	s_waitcnt lgkmcnt(0)
	s_waitcnt lgkmcnt(0)
	s_waitcnt lgkmcnt(0)
	s_waitcnt lgkmcnt(0)
	s_waitcnt lgkmcnt(0)
	s_waitcnt lgkmcnt(0)
	s_waitcnt vmcnt(0)
	s_waitcnt lgkmcnt(0)
	s_waitcnt lgkmcnt(0)
	s_waitcnt lgkmcnt(0)
	s_waitcnt lgkmcnt(0)
	s_waitcnt lgkmcnt(0)
	s_waitcnt lgkmcnt(0)
	s_waitcnt lgkmcnt(0)
	s_waitcnt lgkmcnt(0)
	s_waitcnt vmcnt(0)
	s_waitcnt lgkmcnt(0)
	s_waitcnt lgkmcnt(0)
	s_waitcnt vmcnt(0)
	s_waitcnt lgkmcnt(0)
	s_waitcnt lgkmcnt(0)
	s_waitcnt vmcnt(0)
	s_waitcnt lgkmcnt(0)
	s_waitcnt lgkmcnt(0)
	s_waitcnt vmcnt(0)
	s_waitcnt lgkmcnt(0)
	s_waitcnt lgkmcnt(0)
	s_waitcnt vmcnt(0)
	s_waitcnt lgkmcnt(0)
	s_waitcnt lgkmcnt(0)
	s_waitcnt lgkmcnt(0)
	s_waitcnt lgkmcnt(0)
	s_waitcnt lgkmcnt(0)
	s_waitcnt lgkmcnt(0)
	s_waitcnt lgkmcnt(0)
	s_waitcnt lgkmcnt(0)
	s_waitcnt vmcnt(0)
	s_waitcnt lgkmcnt(0)
	s_waitcnt lgkmcnt(0)
	s_waitcnt lgkmcnt(0)
	s_waitcnt lgkmcnt(0)
	s_waitcnt lgkmcnt(0)
	s_waitcnt lgkmcnt(0)
	s_waitcnt lgkmcnt(0)
	s_waitcnt lgkmcnt(0)
	s_waitcnt vmcnt(0)
	s_waitcnt lgkmcnt(0)
	s_waitcnt lgkmcnt(0)
	s_nop 0
	s_waitcnt vmcnt(0)
	s_nop 0
	s_waitcnt lgkmcnt(0)
	s_waitcnt lgkmcnt(0)
	s_waitcnt lgkmcnt(0)
	s_waitcnt lgkmcnt(0)
	s_waitcnt lgkmcnt(0)
	s_waitcnt lgkmcnt(0)
	s_waitcnt vmcnt(0)
	s_waitcnt vmcnt(0)
	s_waitcnt vmcnt(0)
	s_waitcnt vmcnt(0)
	s_branch .Lsmx_end

; #define LAS __attribute__((address_space(3)))
; __device__ __forceinline__ void sample_mix_even(Frame& F0, int j, int b) {
;     ...
;         const int c = tid + 512 * k, g = c >> 8, win = 2 << g; const float xa = z[c];
;         const float* st = FIN(3) + ((size_t)(j * 128 + b) * 15) * 1024 + c;
;         float sr[15];
; #pragma unroll
;         for (int r = 0; r < 15; ++r) sr[r] = st[(size_t)r * 1024];
;         float s = xa;
; #pragma unroll
;         for (int r = 0; r < 15; ++r) s += (r >= 16 - win) ? sr[r] : 0.f;
;         pl[c] = s / (float)win - xa;
;         float* po = F.out + O_POOLS + ((size_t)(j * 128 + b) * 15) * 1024 + c;
; #pragma unroll
;         for (int r = 0; r < 14; ++r) po[(size_t)r * 1024] = sr[r + 1];
;         po[(size_t)14 * 1024] = xa;
;     ...
;         const bf16_t* pm = ((bf16_t*)(F.ws + WS_PMT)) + (size_t)(j * 4 + g) * 65536 + (size_t)dd * 256; const LAS float* pg = pl + g * 256;
.LBB0_1605:
	s_or_b64 exec, exec, s[4:5]
	s_cmp_eq_u32 s100, 0
	s_cbranch_scc0 .Lpool_hi
	s_load_dwordx2 s[6:7], s[14:15], 0x18
	s_mov_b64 s[4:5], 0x1b100000
	s_add_i32 s16, s19, s93
	v_lshl_add_u64 v[50:51], v[0:1], 0, s[4:5]
	s_mul_hi_i32 s5, s16, 0x3c00
	s_mul_i32 s4, s16, 0x3c00
	s_waitcnt lgkmcnt(0)
	v_mov_b64_e32 v[0:1], s[6:7]
	v_lshl_add_u64 v[0:1], s[4:5], 2, v[0:1]
	v_lshl_add_u64 v[0:1], v[48:49], 2, v[0:1]
	s_mov_b32 s6, 0x8000
	s_nop 0
	v_add_co_u32_e32 v4, vcc, s70, v0
	global_load_dword v27, v[50:51], off
	s_nop 0
	v_addc_co_u32_e32 v5, vcc, 0, v1, vcc
	global_load_dword v29, v[4:5], off offset:-4096
	global_load_dword v30, v[4:5], off
	v_add_co_u32_e32 v8, vcc, s94, v0
	v_ashrrev_i32_e32 v26, 8, v48
	s_nop 0
	v_addc_co_u32_e32 v9, vcc, 0, v1, vcc
	global_load_dword v31, v[8:9], off offset:-4096
	global_load_dword v32, v[8:9], off
	v_add_co_u32_e32 v12, vcc, s71, v0
	s_ashr_i32 s17, s16, 31
	s_nop 0
	v_addc_co_u32_e32 v13, vcc, 0, v1, vcc
	global_load_dword v34, v[12:13], off offset:-4096
	global_load_dword v35, v[12:13], off
	v_add_co_u32_e32 v16, vcc, s6, v0
	s_mov_b32 s6, 0x9000
	s_nop 0
	v_addc_co_u32_e32 v17, vcc, 0, v1, vcc
	s_mov_b32 s6, 0xa000
	s_nop 0
	v_add_co_u32_e32 v22, vcc, s6, v0
	s_mov_b32 s6, 0xc000
	s_nop 0
	v_addc_co_u32_e32 v23, vcc, 0, v1, vcc
	v_add_co_u32_e32 v20, vcc, 0xb000, v0
	global_load_dword v36, v[16:17], off offset:-4096
	global_load_dword v37, v[16:17], off
	v_addc_co_u32_e32 v21, vcc, 0, v1, vcc
	global_load_dword v39, v[22:23], off offset:-4096
	global_load_dword v40, v[22:23], off
	global_load_dword v38, v[20:21], off
	v_add_co_u32_e32 v20, vcc, s6, v0
	s_nop 0
	s_nop 0
	v_addc_co_u32_e32 v21, vcc, 0, v1, vcc
	v_add_co_u32_e32 v24, vcc, 0xd000, v0
	global_load_dword v41, v[20:21], off
	s_nop 0
	v_addc_co_u32_e32 v25, vcc, 0, v1, vcc
	global_load_dword v42, v[24:25], off
	v_add_co_u32_e32 v24, vcc, 0xe000, v0
	s_nop 0
	s_nop 1
	v_addc_co_u32_e32 v25, vcc, 0, v1, vcc
	global_load_dword v43, v[24:25], off
	v_lshlrev_b32_e64 v24, v26, 2
	v_cmp_lt_i32_e32 vcc, 15, v24
	v_mov_b32_e32 v25, 0
	s_and_saveexec_b64 s[6:7], vcc
	global_load_dword v25, v[0:1], off
	s_or_b64 exec, exec, s[6:7]
	v_cmp_lt_i32_e32 vcc, 14, v24
	s_waitcnt vmcnt(0)
	v_add_f32_e32 v25, v27, v25
	v_mov_b64_e32 v[44:45], s[2:3]
	v_cndmask_b32_e32 v33, 0, v29, vcc
	v_cmp_lt_i32_e32 vcc, 13, v24
	v_add_f32_e32 v25, v33, v25
	v_lshl_add_u64 v[44:45], s[4:5], 2, v[44:45]
	v_cndmask_b32_e32 v33, 0, v30, vcc
	v_cmp_lt_i32_e32 vcc, 12, v24
	v_add_f32_e32 v25, v33, v25
	v_add_u32_e32 v61, 0x200, v48
	v_cndmask_b32_e32 v33, 0, v31, vcc
	v_cmp_lt_i32_e32 vcc, 11, v24
	v_add_f32_e32 v25, v33, v25
	v_ashrrev_i32_e32 v62, 8, v61
	v_cndmask_b32_e32 v33, 0, v32, vcc
	v_cmp_lt_i32_e32 vcc, 10, v24
	v_add_f32_e32 v25, v33, v25
	s_nop 0
	v_cndmask_b32_e32 v33, 0, v34, vcc
	v_cmp_lt_i32_e32 vcc, 9, v24
	v_add_f32_e32 v25, v33, v25
	s_nop 0
	v_cndmask_b32_e32 v33, 0, v35, vcc
	v_cmp_lt_i32_e32 vcc, 8, v24
	v_add_f32_e32 v25, v33, v25
	s_nop 0
	v_cndmask_b32_e32 v33, 0, v36, vcc
	v_cmp_lt_i32_e32 vcc, 7, v24
	v_add_f32_e32 v25, v33, v25
	s_nop 0
	v_cndmask_b32_e32 v33, 0, v37, vcc
	v_cmp_lt_i32_e32 vcc, 6, v24
	v_add_f32_e32 v25, v33, v25
	s_nop 0
	v_cndmask_b32_e32 v33, 0, v39, vcc
	v_cmp_lt_i32_e32 vcc, 5, v24
	v_add_f32_e32 v25, v33, v25
	s_nop 0
	v_cndmask_b32_e32 v33, 0, v40, vcc
	v_cmp_lt_i32_e32 vcc, 4, v24
	v_add_f32_e32 v25, v33, v25
	s_nop 0
	v_cndmask_b32_e32 v33, 0, v38, vcc
	v_cmp_lt_i32_e32 vcc, 3, v24
	v_add_f32_e32 v25, v33, v25
	s_nop 0
	v_cndmask_b32_e32 v33, 0, v41, vcc
	v_cmp_lt_i32_e32 vcc, 2, v24
	v_add_f32_e32 v25, v33, v25
	s_nop 0
	v_cndmask_b32_e32 v33, 0, v42, vcc
	v_cmp_lt_i32_e32 vcc, 1, v24
	v_cvt_f32_i32_e32 v24, v24
	v_add_f32_e32 v25, v33, v25
	v_cndmask_b32_e32 v33, 0, v43, vcc
	v_add_f32_e32 v25, v33, v25
	v_div_scale_f32 v33, s[4:5], v24, v24, v25
	v_rcp_f32_e32 v46, v33
	s_mov_b32 s4, 0x4171000
	v_fma_f32 v47, -v33, v46, 1.0
	v_fmac_f32_e32 v46, v47, v46
	v_div_scale_f32 v47, vcc, v25, v24, v25
	v_mul_f32_e32 v52, v47, v46
	v_fma_f32 v53, -v33, v52, v47
	v_fmac_f32_e32 v52, v53, v46
	v_fma_f32 v33, -v33, v52, v47
	v_div_fmas_f32 v33, v33, v46, v52
	v_div_fixup_f32 v24, v33, v24, v25
	v_sub_f32_e32 v24, v24, v27
	v_lshl_add_u32 v33, v48, 2, 0
	ds_write_b32 v33, v24
	v_lshl_add_u64 v[24:25], v[48:49], 2, v[44:45]
	v_add_co_u32_e32 v44, vcc, s4, v24
	s_mov_b32 s4, 0x4173000
	s_nop 0
	v_addc_co_u32_e32 v45, vcc, 0, v25, vcc
	global_store_dword v[44:45], v29, off offset:-4096
	global_store_dword v[44:45], v30, off
	v_add_co_u32_e32 v44, vcc, s4, v24
	s_mov_b32 s4, 0x4175000
	s_nop 0
	v_addc_co_u32_e32 v45, vcc, 0, v25, vcc
	v_add_co_u32_e32 v30, vcc, s4, v24
	global_store_dword v[44:45], v31, off offset:-4096
	global_store_dword v[44:45], v32, off
	v_addc_co_u32_e32 v31, vcc, 0, v25, vcc
	s_mov_b32 s4, 0x4177000
	global_store_dword v[30:31], v34, off offset:-4096
	global_store_dword v[30:31], v35, off
	v_add_co_u32_e32 v30, vcc, s4, v24
	s_mov_b32 s4, 0x4179000
	s_nop 0
	v_addc_co_u32_e32 v31, vcc, 0, v25, vcc
	global_store_dword v[30:31], v36, off offset:-4096
	global_store_dword v[30:31], v37, off
	v_add_co_u32_e32 v30, vcc, s4, v24
	s_mov_b32 s4, 0x417b000
	s_nop 0
	v_addc_co_u32_e32 v31, vcc, 0, v25, vcc
	global_store_dword v[30:31], v39, off offset:-4096
	global_store_dword v[30:31], v40, off
	v_add_co_u32_e32 v30, vcc, s4, v24
	s_mov_b32 s4, 0x417d000
	s_nop 0
	v_addc_co_u32_e32 v31, vcc, 0, v25, vcc
	global_store_dword v[30:31], v38, off offset:-4096
	global_store_dword v[30:31], v41, off
	v_add_co_u32_e32 v30, vcc, s4, v24
	s_mov_b32 s4, 0x417e000
	s_nop 0
	v_addc_co_u32_e32 v31, vcc, 0, v25, vcc
	global_store_dword v[30:31], v42, off offset:-4096
	global_store_dword v[30:31], v43, off
	v_add_co_u32_e32 v30, vcc, s4, v24
	s_nop 0
	s_nop 1
	v_addc_co_u32_e32 v31, vcc, 0, v25, vcc
	global_store_dword v[30:31], v27, off
	s_nop 0
	s_nop 0
	s_nop 0
	s_nop 1
	s_nop 0
	s_nop 1
	v_lshlrev_b32_e64 v13, v62, 2
	v_cmp_lt_i32_e32 vcc, 15, v13
	s_and_saveexec_b64 s[4:5], vcc
	s_mov_b64 s[6:7], 0x800
	s_or_b64 exec, exec, s[4:5]
	s_waitcnt vmcnt(0)
	v_readlane_b32 s24, v254, 49
	s_nop 1
	v_add_u32_e32 v54, s24, v26
	v_ashrrev_i32_e32 v55, 31, v54
	v_readlane_b32 s25, v254, 50
	s_nop 0
	s_nop 0
	s_nop 0
	s_nop 0
	s_nop 0
	s_nop 0
	s_nop 0
	s_nop 0
	s_nop 0
	s_mov_b64 s[4:5], 0x4170000
	s_mov_b32 s4, 0x8000
	s_nop 0
	s_nop 0
	s_nop 0
	s_nop 1
	s_nop 1
	s_nop 1
	s_nop 1
	s_mov_b32 s4, 0x9000
	s_nop 0
	s_mov_b32 s4, 0xa000
	s_nop 0
	s_mov_b32 s4, 0xb000
	s_nop 0
	s_mov_b32 s4, 0xc000
	s_nop 0
	s_mov_b32 s4, 0xd000
	s_nop 0
	s_mov_b32 s4, 0xe000
	s_nop 0
	s_mov_b64 s[4:5], 0x6600000
	s_nop 0
	v_lshlrev_b32_e32 v0, 9, v48
	v_and_b32_e32 v200, 0x1fe00, v0
	v_lshl_add_u64 v[0:1], s[12:13], 0, v[200:201]
	v_lshl_add_u64 v[52:53], v[0:1], 0, s[4:5]
	v_lshlrev_b64 v[0:1], 17, v[54:55]
	v_lshl_add_u64 v[56:57], v[52:53], 0, v[0:1]
	s_branch .Lpool_join
; __device__ __forceinline__ void sample_mix_even(Frame& F0, int j, int b) {
;     ...
;         const int c = tid + 512 * k, g = c >> 8, win = 2 << g; const float xa = z[c];
;         const float* st = FIN(3) + ((size_t)(j * 128 + b) * 15) * 1024 + c;
;         float sr[15];
; #pragma unroll
;         for (int r = 0; r < 15; ++r) sr[r] = st[(size_t)r * 1024];
.Lpool_hi:
	s_load_dwordx2 s[6:7], s[14:15], 0x18
	s_mov_b64 s[4:5], 0x1b100000
	s_add_i32 s16, s19, s93
	v_lshl_add_u64 v[50:51], v[0:1], 0, s[4:5]
	s_mul_hi_i32 s5, s16, 0x3c00
	s_mul_i32 s4, s16, 0x3c00
	s_waitcnt lgkmcnt(0)
	v_mov_b64_e32 v[0:1], s[6:7]
	v_lshl_add_u64 v[0:1], s[4:5], 2, v[0:1]
	v_lshl_add_u64 v[0:1], v[48:49], 2, v[0:1]
	v_add_co_u32_e32 v2, vcc, s33, v0
	s_mov_b32 s6, 0x8000
	s_nop 0
	v_addc_co_u32_e32 v3, vcc, 0, v1, vcc
	v_add_co_u32_e32 v4, vcc, s70, v0
	s_nop 0
	s_nop 0
	v_addc_co_u32_e32 v5, vcc, 0, v1, vcc
	s_nop 0
	v_add_co_u32_e32 v6, vcc, s95, v0
	s_nop 1
	v_addc_co_u32_e32 v7, vcc, 0, v1, vcc
	v_add_co_u32_e32 v8, vcc, s94, v0
	v_ashrrev_i32_e32 v26, 8, v48
	s_nop 0
	v_addc_co_u32_e32 v9, vcc, 0, v1, vcc
	s_nop 0
	v_add_co_u32_e32 v10, vcc, s81, v0
	s_nop 1
	v_addc_co_u32_e32 v11, vcc, 0, v1, vcc
	v_add_co_u32_e32 v12, vcc, s71, v0
	s_ashr_i32 s17, s16, 31
	s_nop 0
	v_addc_co_u32_e32 v13, vcc, 0, v1, vcc
	s_nop 0
	v_add_co_u32_e32 v14, vcc, s82, v0
	s_nop 1
	v_addc_co_u32_e32 v15, vcc, 0, v1, vcc
	v_add_co_u32_e32 v16, vcc, s6, v0
	s_mov_b32 s6, 0x9000
	s_nop 0
	v_addc_co_u32_e32 v17, vcc, 0, v1, vcc
	v_add_co_u32_e32 v18, vcc, s6, v0
	s_mov_b32 s6, 0xa000
	s_nop 0
	v_addc_co_u32_e32 v19, vcc, 0, v1, vcc
	v_add_co_u32_e32 v22, vcc, s6, v0
	s_mov_b32 s6, 0xc000
	s_nop 0
	v_addc_co_u32_e32 v23, vcc, 0, v1, vcc
	v_add_co_u32_e32 v20, vcc, s6, v0
	v_mov_b32_e32 v28, 0
	s_nop 0
	v_addc_co_u32_e32 v21, vcc, 0, v1, vcc
	s_nop 0
	s_nop 1
	v_lshlrev_b32_e64 v24, v26, 2
	v_cmp_lt_i32_e32 vcc, 15, v24
	s_and_saveexec_b64 s[6:7], vcc
	s_or_b64 exec, exec, s[6:7]
	s_waitcnt vmcnt(0)
	v_mov_b64_e32 v[44:45], s[2:3]
	v_lshl_add_u64 v[44:45], s[4:5], 2, v[44:45]
	v_add_u32_e32 v61, 0x200, v48
	v_ashrrev_i32_e32 v62, 8, v61
	s_nop 0
	s_nop 0
	s_nop 0
	s_nop 0
	s_nop 0
	s_nop 0
	s_nop 0
	s_nop 0
	s_nop 0
	s_mov_b32 s4, 0x4171000
	v_lshl_add_u32 v33, v48, 2, 0
	v_lshl_add_u64 v[24:25], v[48:49], 2, v[44:45]
	s_mov_b32 s4, 0x4173000
	s_nop 0
	s_mov_b32 s4, 0x4175000
	s_nop 0
	s_mov_b32 s4, 0x4177000
	s_mov_b32 s4, 0x4179000
	s_nop 0
	s_mov_b32 s4, 0x417b000
	s_nop 0
	s_mov_b32 s4, 0x417d000
	s_nop 0
	s_mov_b32 s4, 0x417e000
	s_nop 0
	s_nop 1
	global_load_dword v27, v[50:51], off offset:2048
	s_nop 0
	global_load_dword v31, v[2:3], off offset:2048
	global_load_dword v30, v[4:5], off offset:2048
	global_load_dword v29, v[6:7], off offset:2048
	s_nop 0
	global_load_dword v8, v[8:9], off offset:2048
	s_nop 0
	global_load_dword v7, v[10:11], off offset:2048
	global_load_dword v6, v[12:13], off offset:2048
	global_load_dword v5, v[14:15], off offset:2048
	global_load_dword v4, v[16:17], off offset:2048
	global_load_dword v3, v[18:19], off offset:2048
	global_load_dword v2, v[22:23], off offset:2048
	v_add_co_u32_e32 v10, vcc, 0xb000, v0
	s_nop 0
	s_nop 1
	v_addc_co_u32_e32 v11, vcc, 0, v1, vcc
	v_add_co_u32_e32 v12, vcc, 0xd000, v0
	global_load_dword v10, v[10:11], off offset:2048
	s_nop 0
	global_load_dword v9, v[20:21], off offset:2048
	v_addc_co_u32_e32 v13, vcc, 0, v1, vcc
	global_load_dword v11, v[12:13], off offset:2048
	v_add_co_u32_e32 v12, vcc, 0xe000, v0
	s_nop 0
	s_nop 1
	v_addc_co_u32_e32 v13, vcc, 0, v1, vcc
	global_load_dword v12, v[12:13], off offset:2048
	v_lshlrev_b32_e64 v13, v62, 2
	v_cmp_lt_i32_e32 vcc, 15, v13
	s_and_saveexec_b64 s[4:5], vcc
	s_mov_b64 s[6:7], 0x800
	v_lshl_add_u64 v[0:1], v[0:1], 0, s[6:7]
	global_load_dword v28, v[0:1], off
	s_or_b64 exec, exec, s[4:5]
	v_cmp_lt_i32_e32 vcc, 14, v13
	s_waitcnt vmcnt(0)
; #define LAS __attribute__((address_space(3)))
; __device__ __forceinline__ void sample_mix_even(Frame& F0, int j, int b) {
;     ...
;         float s = xa;
; #pragma unroll
;         for (int r = 0; r < 15; ++r) s += (r >= 16 - win) ? sr[r] : 0.f;
;         pl[c] = s / (float)win - xa;
;         float* po = F.out + O_POOLS + ((size_t)(j * 128 + b) * 15) * 1024 + c;
; #pragma unroll
;         for (int r = 0; r < 14; ++r) po[(size_t)r * 1024] = sr[r + 1];
;         po[(size_t)14 * 1024] = xa;
;     }
;     ...
;         const bf16_t* pm = ((bf16_t*)(F.ws + WS_PMT)) + (size_t)(j * 4 + g) * 65536 + (size_t)dd * 256; const LAS float* pg = pl + g * 256;
	v_add_f32_e32 v28, v27, v28
	v_readlane_b32 s24, v254, 49
	v_cndmask_b32_e32 v0, 0, v31, vcc
	v_cmp_lt_i32_e32 vcc, 13, v13
	v_add_f32_e32 v0, v0, v28
	v_add_u32_e32 v54, s24, v26
	v_cndmask_b32_e32 v1, 0, v30, vcc
	v_cmp_lt_i32_e32 vcc, 12, v13
	v_add_f32_e32 v0, v1, v0
	v_ashrrev_i32_e32 v55, 31, v54
	v_cndmask_b32_e32 v14, 0, v29, vcc
	v_cmp_lt_i32_e32 vcc, 11, v13
	v_add_f32_e32 v0, v14, v0
	v_readlane_b32 s25, v254, 50
	v_cndmask_b32_e32 v15, 0, v8, vcc
	v_cmp_lt_i32_e32 vcc, 10, v13
	v_add_f32_e32 v0, v15, v0
	s_nop 0
	v_cndmask_b32_e32 v16, 0, v7, vcc
	v_cmp_lt_i32_e32 vcc, 9, v13
	v_add_f32_e32 v0, v16, v0
	s_nop 0
	v_cndmask_b32_e32 v17, 0, v6, vcc
	v_cmp_lt_i32_e32 vcc, 8, v13
	v_add_f32_e32 v0, v17, v0
	s_nop 0
	v_cndmask_b32_e32 v18, 0, v5, vcc
	v_cmp_lt_i32_e32 vcc, 7, v13
	v_add_f32_e32 v0, v18, v0
	s_nop 0
	v_cndmask_b32_e32 v19, 0, v4, vcc
	v_cmp_lt_i32_e32 vcc, 6, v13
	v_add_f32_e32 v0, v19, v0
	s_nop 0
	v_cndmask_b32_e32 v20, 0, v3, vcc
	v_cmp_lt_i32_e32 vcc, 5, v13
	v_add_f32_e32 v0, v20, v0
	s_nop 0
	v_cndmask_b32_e32 v21, 0, v2, vcc
	v_cmp_lt_i32_e32 vcc, 4, v13
	v_add_f32_e32 v0, v21, v0
	s_nop 0
	v_cndmask_b32_e32 v22, 0, v10, vcc
	v_cmp_lt_i32_e32 vcc, 3, v13
	v_add_f32_e32 v0, v22, v0
	s_nop 0
	v_cndmask_b32_e32 v23, 0, v9, vcc
	v_cmp_lt_i32_e32 vcc, 2, v13
	v_add_f32_e32 v0, v23, v0
	s_nop 0
	v_cndmask_b32_e32 v32, 0, v11, vcc
	v_cmp_lt_i32_e32 vcc, 1, v13
	v_cvt_f32_i32_e32 v13, v13
	v_add_f32_e32 v0, v32, v0
	v_cndmask_b32_e32 v34, 0, v12, vcc
	v_add_f32_e32 v14, v34, v0
	v_div_scale_f32 v15, s[4:5], v13, v13, v14
	v_rcp_f32_e32 v16, v15
	s_mov_b64 s[4:5], 0x4170000
	v_lshl_add_u64 v[0:1], v[24:25], 0, s[4:5]
	s_mov_b32 s4, 0x8000
	v_fma_f32 v17, -v15, v16, 1.0
	v_fmac_f32_e32 v16, v17, v16
	v_div_scale_f32 v17, vcc, v14, v13, v14
	v_mul_f32_e32 v18, v17, v16
	v_fma_f32 v19, -v15, v18, v17
	v_fmac_f32_e32 v18, v19, v16
	v_fma_f32 v15, -v15, v18, v17
	v_div_fmas_f32 v15, v15, v16, v18
	v_div_fixup_f32 v13, v15, v13, v14
	v_add_co_u32_e32 v14, vcc, s33, v0
	global_store_dword v[0:1], v31, off offset:2048
	s_nop 0
	v_addc_co_u32_e32 v15, vcc, 0, v1, vcc
	global_store_dword v[14:15], v30, off offset:2048
	v_add_co_u32_e32 v14, vcc, s70, v0
	v_sub_f32_e32 v13, v13, v27
	s_nop 0
	v_addc_co_u32_e32 v15, vcc, 0, v1, vcc
	global_store_dword v[14:15], v29, off offset:2048
	v_add_co_u32_e32 v14, vcc, s95, v0
	ds_write_b32 v33, v13 offset:2048
	s_nop 0
	v_addc_co_u32_e32 v15, vcc, 0, v1, vcc
	global_store_dword v[14:15], v8, off offset:2048
	v_add_co_u32_e32 v14, vcc, s94, v0
	s_nop 0
	s_nop 1
	v_addc_co_u32_e32 v15, vcc, 0, v1, vcc
	global_store_dword v[14:15], v7, off offset:2048
	v_add_co_u32_e32 v14, vcc, s81, v0
	s_nop 0
	s_nop 1
	v_addc_co_u32_e32 v15, vcc, 0, v1, vcc
	global_store_dword v[14:15], v6, off offset:2048
	v_add_co_u32_e32 v6, vcc, s71, v0
	s_nop 0
	s_nop 1
	v_addc_co_u32_e32 v7, vcc, 0, v1, vcc
	global_store_dword v[6:7], v5, off offset:2048
	v_add_co_u32_e32 v6, vcc, s82, v0
	s_nop 0
	s_nop 1
	v_addc_co_u32_e32 v7, vcc, 0, v1, vcc
	global_store_dword v[6:7], v4, off offset:2048
	v_add_co_u32_e32 v4, vcc, s4, v0
	s_mov_b32 s4, 0x9000
	s_nop 0
	v_addc_co_u32_e32 v5, vcc, 0, v1, vcc
	global_store_dword v[4:5], v3, off offset:2048
	v_add_co_u32_e32 v4, vcc, s4, v0
	s_mov_b32 s4, 0xa000
	s_nop 0
	v_addc_co_u32_e32 v5, vcc, 0, v1, vcc
	global_store_dword v[4:5], v2, off offset:2048
	v_add_co_u32_e32 v2, vcc, s4, v0
	s_mov_b32 s4, 0xb000
	s_nop 0
	v_addc_co_u32_e32 v3, vcc, 0, v1, vcc
	global_store_dword v[2:3], v10, off offset:2048
	v_add_co_u32_e32 v2, vcc, s4, v0
	s_mov_b32 s4, 0xc000
	s_nop 0
	v_addc_co_u32_e32 v3, vcc, 0, v1, vcc
	global_store_dword v[2:3], v9, off offset:2048
	v_add_co_u32_e32 v2, vcc, s4, v0
	s_mov_b32 s4, 0xd000
	s_nop 0
	v_addc_co_u32_e32 v3, vcc, 0, v1, vcc
	global_store_dword v[2:3], v11, off offset:2048
	v_add_co_u32_e32 v2, vcc, s4, v0
	s_mov_b32 s4, 0xe000
	s_nop 0
	v_addc_co_u32_e32 v3, vcc, 0, v1, vcc
	v_add_co_u32_e32 v0, vcc, s4, v0
	s_mov_b64 s[4:5], 0x6600000
	s_nop 0
	v_addc_co_u32_e32 v1, vcc, 0, v1, vcc
	global_store_dword v[0:1], v27, off offset:2048
	v_lshlrev_b32_e32 v0, 9, v48
	v_and_b32_e32 v200, 0x1fe00, v0
	v_lshl_add_u64 v[0:1], s[12:13], 0, v[200:201]
	v_lshl_add_u64 v[52:53], v[0:1], 0, s[4:5]
	v_lshlrev_b64 v[0:1], 17, v[54:55]
	v_lshl_add_u64 v[56:57], v[52:53], 0, v[0:1]
	global_store_dword v[2:3], v12, off offset:2048
	s_branch .Lpool_join
